# grid barrier: non-leader workgroups poll the top-level generation word directly (one hand-off hop less)
# speedup vs baseline: 1.0029x; 1.0003x over previous
; #define LAS __attribute__((address_space(3)))
; DI int ltid(int wv) { asm volatile("" : "+s"(wv)); int l = __builtin_amdgcn_mbcnt_hi(~0u, __builtin_amdgcn_mbcnt_lo(~0u, 0u)); asm volatile("" : "+v"(l)); return wv * 64 + l; }
; DI unsigned xb_ld(unsigned* p) { return __hip_atomic_load(p, __ATOMIC_RELAXED, __HIP_MEMORY_SCOPE_AGENT); }
; DI unsigned xb_add(unsigned* p, unsigned v) { return __hip_atomic_fetch_add(p, v, __ATOMIC_RELAXED, __HIP_MEMORY_SCOPE_AGENT); }
; DI unsigned xb_xcc_id() { return (unsigned)__builtin_amdgcn_s_getreg((3 << 11) | 20) & 0xFu; }
; #define XB_SPIN(cond, bar) do { unsigned _sp = 0; while (cond) { __builtin_amdgcn_s_sleep(1); \
;     if ((++_sp & 255u) == 0u) { if (xb_ld(&(bar)[XB_TMO])) break; if (_sp > XB_SPIN_CAP) { atomicAdd(&(bar)[XB_TMO], 1u); break; } } } } while (0)
; DI void xcd_barrier(int wv, unsigned* bar, volatile LAS unsigned* st) {
;     asm volatile("s_waitcnt vmcnt(0)" ::: "memory");
;     __syncthreads();
;     if (ltid(wv) == 0) {
;         const unsigned x = xb_xcc_id();
;         __builtin_amdgcn_s_waitcnt(0);
;         unsigned nloc = st[0], nx = st[1];
;         if (nloc == 0u) { xcd_barrier_complete(bar, x, nloc, nx); st[0] = nloc; st[1] = nx; }
;         const unsigned old = xb_add(&bar[XB_XSUB(x)], 1u);
;         const unsigned gen = old / nloc;
;         if (old + 1u == (gen + 1u) * nloc) {
;             __builtin_amdgcn_fence(__ATOMIC_RELEASE, "agent");
;             asm volatile("s_waitcnt vmcnt(0)" ::: "memory");
;             const unsigned og = xb_add(&bar[XB_TOP], 1u);
;             const unsigned tg = og / nx;
;             if (og + 1u == (tg + 1u) * nx) xb_add(&bar[XB_TOPGEN], 1u);
;             else XB_SPIN(xb_ld(&bar[XB_TOPGEN]) == tg, bar);
;             __builtin_amdgcn_fence(__ATOMIC_ACQUIRE, "agent");
;             xb_add(&bar[XB_XGEN(x)], 1u);
;             asm volatile("s_waitcnt vmcnt(0)" ::: "memory");
;         } else {
;             XB_SPIN(xb_ld(&bar[XB_XGEN(x)]) == gen, bar);
;             __builtin_amdgcn_fence(__ATOMIC_ACQUIRE, "agent");
;             asm volatile("s_waitcnt vmcnt(0)" ::: "memory");
;         }
.LBB0_334:
	s_or_b64 exec, exec, s[8:9]
	v_cvt_f32_u32_e32 v4, v2
	s_waitcnt vmcnt(0)
	v_readfirstlane_b32 s6, v3
	v_sub_u32_e32 v3, 0, v2
	v_rcp_iflag_f32_e32 v4, v4
	v_add_u32_e32 v5, s6, v1
	v_mul_f32_e32 v4, 0x4f7ffffe, v4
	v_cvt_u32_f32_e32 v4, v4
	v_mul_lo_u32 v1, v3, v4
	v_mul_hi_u32 v1, v4, v1
	v_add_u32_e32 v1, v4, v1
	v_mul_hi_u32 v1, v5, v1
	v_mul_lo_u32 v3, v1, v2
	v_sub_u32_e32 v3, v5, v3
	v_add_u32_e32 v4, 1, v1
	v_cmp_ge_u32_e32 vcc, v3, v2
	s_nop 1
	v_cndmask_b32_e32 v1, v1, v4, vcc
	v_sub_u32_e32 v4, v3, v2
	v_cndmask_b32_e32 v3, v3, v4, vcc
	v_add_u32_e32 v4, 1, v1
	v_cmp_ge_u32_e32 vcc, v3, v2
	v_add_u32_e32 v3, 1, v5
	s_nop 0
	v_cndmask_b32_e32 v1, v1, v4, vcc
	v_mul_lo_u32 v4, v2, v1
	v_add_u32_e32 v2, v4, v2
	v_cmp_ne_u32_e32 vcc, v3, v2
	s_and_saveexec_b64 s[6:7], vcc
	s_xor_b64 s[6:7], exec, s[6:7]
	s_cbranch_execz .LBB0_348
	s_waitcnt lgkmcnt(0)
	v_mov_b32_e32 v0, 0
	s_lshl_b32 s12, s47, 8
	s_sub_u32 s12, s4, s12
	s_subb_u32 s13, s5, 0
	s_add_u32 s12, s12, 0x3500
	s_addc_u32 s13, s13, 0
	global_load_dword v0, v0, s[12:13] sc1
	s_waitcnt vmcnt(0)
	v_cmp_eq_u32_e32 vcc, v0, v1
	s_and_saveexec_b64 s[8:9], vcc
	s_cbranch_execz .LBB0_347
	s_add_u32 s10, s2, 0x1d83200
	s_addc_u32 s11, s3, 0
	s_mov_b32 s24, 1
	s_mov_b64 s[14:15], 0
	v_mov_b32_e32 v0, 0
	s_branch .LBB0_338

; #define LAS __attribute__((address_space(3)))
; DI int ltid(int wv) { asm volatile("" : "+s"(wv)); int l = __builtin_amdgcn_mbcnt_hi(~0u, __builtin_amdgcn_mbcnt_lo(~0u, 0u)); asm volatile("" : "+v"(l)); return wv * 64 + l; }
; DI unsigned xb_ld(unsigned* p) { return __hip_atomic_load(p, __ATOMIC_RELAXED, __HIP_MEMORY_SCOPE_AGENT); }
; DI unsigned xb_add(unsigned* p, unsigned v) { return __hip_atomic_fetch_add(p, v, __ATOMIC_RELAXED, __HIP_MEMORY_SCOPE_AGENT); }
; DI unsigned xb_xcc_id() { return (unsigned)__builtin_amdgcn_s_getreg((3 << 11) | 20) & 0xFu; }
; #define XB_SPIN(cond, bar) do { unsigned _sp = 0; while (cond) { __builtin_amdgcn_s_sleep(1); \
;     if ((++_sp & 255u) == 0u) { if (xb_ld(&(bar)[XB_TMO])) break; if (_sp > XB_SPIN_CAP) { atomicAdd(&(bar)[XB_TMO], 1u); break; } } } } while (0)
; DI void xcd_barrier(int wv, unsigned* bar, volatile LAS unsigned* st) {
;     asm volatile("s_waitcnt vmcnt(0)" ::: "memory");
;     __syncthreads();
;     if (ltid(wv) == 0) {
;         const unsigned x = xb_xcc_id();
;         __builtin_amdgcn_s_waitcnt(0);
;         unsigned nloc = st[0], nx = st[1];
;         if (nloc == 0u) { xcd_barrier_complete(bar, x, nloc, nx); st[0] = nloc; st[1] = nx; }
;         const unsigned old = xb_add(&bar[XB_XSUB(x)], 1u);
;         const unsigned gen = old / nloc;
;         if (old + 1u == (gen + 1u) * nloc) {
;             __builtin_amdgcn_fence(__ATOMIC_RELEASE, "agent");
;             asm volatile("s_waitcnt vmcnt(0)" ::: "memory");
;             const unsigned og = xb_add(&bar[XB_TOP], 1u);
;             const unsigned tg = og / nx;
;             if (og + 1u == (tg + 1u) * nx) xb_add(&bar[XB_TOPGEN], 1u);
;             else XB_SPIN(xb_ld(&bar[XB_TOPGEN]) == tg, bar);
;             __builtin_amdgcn_fence(__ATOMIC_ACQUIRE, "agent");
;             xb_add(&bar[XB_XGEN(x)], 1u);
;             asm volatile("s_waitcnt vmcnt(0)" ::: "memory");
;         } else {
;             XB_SPIN(xb_ld(&bar[XB_XGEN(x)]) == gen, bar);
;             __builtin_amdgcn_fence(__ATOMIC_ACQUIRE, "agent");
;             asm volatile("s_waitcnt vmcnt(0)" ::: "memory");
;         }
.LBB0_487:
	s_or_b64 exec, exec, s[8:9]
	v_cvt_f32_u32_e32 v4, v2
	s_waitcnt vmcnt(0)
	v_readfirstlane_b32 s6, v3
	v_sub_u32_e32 v3, 0, v2
	v_rcp_iflag_f32_e32 v4, v4
	v_add_u32_e32 v5, s6, v1
	v_mul_f32_e32 v4, 0x4f7ffffe, v4
	v_cvt_u32_f32_e32 v4, v4
	v_mul_lo_u32 v1, v3, v4
	v_mul_hi_u32 v1, v4, v1
	v_add_u32_e32 v1, v4, v1
	v_mul_hi_u32 v1, v5, v1
	v_mul_lo_u32 v3, v1, v2
	v_sub_u32_e32 v3, v5, v3
	v_add_u32_e32 v4, 1, v1
	v_cmp_ge_u32_e32 vcc, v3, v2
	s_nop 1
	v_cndmask_b32_e32 v1, v1, v4, vcc
	v_sub_u32_e32 v4, v3, v2
	v_cndmask_b32_e32 v3, v3, v4, vcc
	v_add_u32_e32 v4, 1, v1
	v_cmp_ge_u32_e32 vcc, v3, v2
	v_add_u32_e32 v3, 1, v5
	s_nop 0
	v_cndmask_b32_e32 v1, v1, v4, vcc
	v_mul_lo_u32 v4, v2, v1
	v_add_u32_e32 v2, v4, v2
	v_cmp_ne_u32_e32 vcc, v3, v2
	s_and_saveexec_b64 s[6:7], vcc
	s_xor_b64 s[6:7], exec, s[6:7]
	s_cbranch_execz .LBB0_501
	s_waitcnt lgkmcnt(0)
	v_mov_b32_e32 v0, 0
	s_lshl_b32 s12, s33, 8
	s_sub_u32 s12, s4, s12
	s_subb_u32 s13, s5, 0
	s_add_u32 s12, s12, 0x3500
	s_addc_u32 s13, s13, 0
	global_load_dword v0, v0, s[12:13] sc1
	s_waitcnt vmcnt(0)
	v_cmp_eq_u32_e32 vcc, v0, v1
	s_and_saveexec_b64 s[8:9], vcc
	s_cbranch_execz .LBB0_500
	s_add_u32 s10, s2, 0x1d83200
	s_addc_u32 s11, s3, 0
	s_mov_b32 s24, 1
	s_mov_b64 s[14:15], 0
	v_mov_b32_e32 v0, 0
	s_branch .LBB0_491

; #define LAS __attribute__((address_space(3)))
; DI int ltid(int wv) { asm volatile("" : "+s"(wv)); int l = __builtin_amdgcn_mbcnt_hi(~0u, __builtin_amdgcn_mbcnt_lo(~0u, 0u)); asm volatile("" : "+v"(l)); return wv * 64 + l; }
; DI unsigned xb_ld(unsigned* p) { return __hip_atomic_load(p, __ATOMIC_RELAXED, __HIP_MEMORY_SCOPE_AGENT); }
; DI unsigned xb_add(unsigned* p, unsigned v) { return __hip_atomic_fetch_add(p, v, __ATOMIC_RELAXED, __HIP_MEMORY_SCOPE_AGENT); }
; DI unsigned xb_xcc_id() { return (unsigned)__builtin_amdgcn_s_getreg((3 << 11) | 20) & 0xFu; }
; #define XB_SPIN(cond, bar) do { unsigned _sp = 0; while (cond) { __builtin_amdgcn_s_sleep(1); \
;     if ((++_sp & 255u) == 0u) { if (xb_ld(&(bar)[XB_TMO])) break; if (_sp > XB_SPIN_CAP) { atomicAdd(&(bar)[XB_TMO], 1u); break; } } } } while (0)
; DI void xcd_barrier(int wv, unsigned* bar, volatile LAS unsigned* st) {
;     asm volatile("s_waitcnt vmcnt(0)" ::: "memory");
;     __syncthreads();
;     if (ltid(wv) == 0) {
;         const unsigned x = xb_xcc_id();
;         __builtin_amdgcn_s_waitcnt(0);
;         unsigned nloc = st[0], nx = st[1];
;         if (nloc == 0u) { xcd_barrier_complete(bar, x, nloc, nx); st[0] = nloc; st[1] = nx; }
;         const unsigned old = xb_add(&bar[XB_XSUB(x)], 1u);
;         const unsigned gen = old / nloc;
;         if (old + 1u == (gen + 1u) * nloc) {
;             __builtin_amdgcn_fence(__ATOMIC_RELEASE, "agent");
;             asm volatile("s_waitcnt vmcnt(0)" ::: "memory");
;             const unsigned og = xb_add(&bar[XB_TOP], 1u);
;             const unsigned tg = og / nx;
;             if (og + 1u == (tg + 1u) * nx) xb_add(&bar[XB_TOPGEN], 1u);
;             else XB_SPIN(xb_ld(&bar[XB_TOPGEN]) == tg, bar);
;             __builtin_amdgcn_fence(__ATOMIC_ACQUIRE, "agent");
;             xb_add(&bar[XB_XGEN(x)], 1u);
;             asm volatile("s_waitcnt vmcnt(0)" ::: "memory");
;         } else {
;             XB_SPIN(xb_ld(&bar[XB_XGEN(x)]) == gen, bar);
;             __builtin_amdgcn_fence(__ATOMIC_ACQUIRE, "agent");
;             asm volatile("s_waitcnt vmcnt(0)" ::: "memory");
;         }
.LBB0_739:
	s_or_b64 exec, exec, s[10:11]
	v_cvt_f32_u32_e32 v4, v2
	s_waitcnt vmcnt(0)
	v_readfirstlane_b32 s8, v3
	v_sub_u32_e32 v3, 0, v2
	v_rcp_iflag_f32_e32 v4, v4
	v_add_u32_e32 v5, s8, v1
	v_mul_f32_e32 v4, 0x4f7ffffe, v4
	v_cvt_u32_f32_e32 v4, v4
	v_mul_lo_u32 v1, v3, v4
	v_mul_hi_u32 v1, v4, v1
	v_add_u32_e32 v1, v4, v1
	v_mul_hi_u32 v1, v5, v1
	v_mul_lo_u32 v3, v1, v2
	v_sub_u32_e32 v3, v5, v3
	v_add_u32_e32 v4, 1, v1
	v_cmp_ge_u32_e32 vcc, v3, v2
	s_nop 1
	v_cndmask_b32_e32 v1, v1, v4, vcc
	v_sub_u32_e32 v4, v3, v2
	v_cndmask_b32_e32 v3, v3, v4, vcc
	v_add_u32_e32 v4, 1, v1
	v_cmp_ge_u32_e32 vcc, v3, v2
	v_add_u32_e32 v3, 1, v5
	s_nop 0
	v_cndmask_b32_e32 v1, v1, v4, vcc
	v_mul_lo_u32 v4, v2, v1
	v_add_u32_e32 v2, v4, v2
	v_cmp_ne_u32_e32 vcc, v3, v2
	s_and_saveexec_b64 s[8:9], vcc
	s_xor_b64 s[8:9], exec, s[8:9]
	s_cbranch_execz .LBB0_753
	s_waitcnt lgkmcnt(0)
	v_mov_b32_e32 v0, 0
	s_lshl_b32 s14, s33, 8
	s_sub_u32 s14, s6, s14
	s_subb_u32 s15, s7, 0
	s_add_u32 s14, s14, 0x3500
	s_addc_u32 s15, s15, 0
	global_load_dword v0, v0, s[14:15] sc1
	s_waitcnt vmcnt(0)
	v_cmp_eq_u32_e32 vcc, v0, v1
	s_and_saveexec_b64 s[10:11], vcc
	s_cbranch_execz .LBB0_752
	s_add_u32 s12, s4, 0x1d83200
	s_addc_u32 s13, s5, 0
	s_mov_b32 s26, 1
	s_mov_b64 s[16:17], 0
	v_mov_b32_e32 v0, 0
	s_branch .LBB0_743

; #define LAS __attribute__((address_space(3)))
; DI int ltid(int wv) { asm volatile("" : "+s"(wv)); int l = __builtin_amdgcn_mbcnt_hi(~0u, __builtin_amdgcn_mbcnt_lo(~0u, 0u)); asm volatile("" : "+v"(l)); return wv * 64 + l; }
; DI unsigned xb_ld(unsigned* p) { return __hip_atomic_load(p, __ATOMIC_RELAXED, __HIP_MEMORY_SCOPE_AGENT); }
; DI unsigned xb_add(unsigned* p, unsigned v) { return __hip_atomic_fetch_add(p, v, __ATOMIC_RELAXED, __HIP_MEMORY_SCOPE_AGENT); }
; DI unsigned xb_xcc_id() { return (unsigned)__builtin_amdgcn_s_getreg((3 << 11) | 20) & 0xFu; }
; #define XB_SPIN(cond, bar) do { unsigned _sp = 0; while (cond) { __builtin_amdgcn_s_sleep(1); \
;     if ((++_sp & 255u) == 0u) { if (xb_ld(&(bar)[XB_TMO])) break; if (_sp > XB_SPIN_CAP) { atomicAdd(&(bar)[XB_TMO], 1u); break; } } } } while (0)
; DI void xcd_barrier(int wv, unsigned* bar, volatile LAS unsigned* st) {
;     asm volatile("s_waitcnt vmcnt(0)" ::: "memory");
;     __syncthreads();
;     if (ltid(wv) == 0) {
;         const unsigned x = xb_xcc_id();
;         __builtin_amdgcn_s_waitcnt(0);
;         unsigned nloc = st[0], nx = st[1];
;         if (nloc == 0u) { xcd_barrier_complete(bar, x, nloc, nx); st[0] = nloc; st[1] = nx; }
;         const unsigned old = xb_add(&bar[XB_XSUB(x)], 1u);
;         const unsigned gen = old / nloc;
;         if (old + 1u == (gen + 1u) * nloc) {
;             __builtin_amdgcn_fence(__ATOMIC_RELEASE, "agent");
;             asm volatile("s_waitcnt vmcnt(0)" ::: "memory");
;             const unsigned og = xb_add(&bar[XB_TOP], 1u);
;             const unsigned tg = og / nx;
;             if (og + 1u == (tg + 1u) * nx) xb_add(&bar[XB_TOPGEN], 1u);
;             else XB_SPIN(xb_ld(&bar[XB_TOPGEN]) == tg, bar);
;             __builtin_amdgcn_fence(__ATOMIC_ACQUIRE, "agent");
;             xb_add(&bar[XB_XGEN(x)], 1u);
;             asm volatile("s_waitcnt vmcnt(0)" ::: "memory");
;         } else {
;             XB_SPIN(xb_ld(&bar[XB_XGEN(x)]) == gen, bar);
;             __builtin_amdgcn_fence(__ATOMIC_ACQUIRE, "agent");
;             asm volatile("s_waitcnt vmcnt(0)" ::: "memory");
;         }
.LBB0_1483:
	s_or_b64 exec, exec, s[10:11]
	v_cvt_f32_u32_e32 v4, v2
	s_waitcnt vmcnt(0)
	v_readfirstlane_b32 s8, v3
	v_sub_u32_e32 v3, 0, v2
	v_rcp_iflag_f32_e32 v4, v4
	v_add_u32_e32 v5, s8, v1
	v_mul_f32_e32 v4, 0x4f7ffffe, v4
	v_cvt_u32_f32_e32 v4, v4
	v_mul_lo_u32 v1, v3, v4
	v_mul_hi_u32 v1, v4, v1
	v_add_u32_e32 v1, v4, v1
	v_mul_hi_u32 v1, v5, v1
	v_mul_lo_u32 v3, v1, v2
	v_sub_u32_e32 v3, v5, v3
	v_add_u32_e32 v4, 1, v1
	v_cmp_ge_u32_e32 vcc, v3, v2
	s_nop 1
	v_cndmask_b32_e32 v1, v1, v4, vcc
	v_sub_u32_e32 v4, v3, v2
	v_cndmask_b32_e32 v3, v3, v4, vcc
	v_add_u32_e32 v4, 1, v1
	v_cmp_ge_u32_e32 vcc, v3, v2
	v_add_u32_e32 v3, 1, v5
	s_nop 0
	v_cndmask_b32_e32 v1, v1, v4, vcc
	v_mul_lo_u32 v4, v2, v1
	v_add_u32_e32 v2, v4, v2
	v_cmp_ne_u32_e32 vcc, v3, v2
	s_and_saveexec_b64 s[8:9], vcc
	s_xor_b64 s[8:9], exec, s[8:9]
	s_cbranch_execz .LBB0_1497
	s_waitcnt lgkmcnt(0)
	v_mov_b32_e32 v0, 0
	s_lshl_b32 s14, s33, 8
	s_sub_u32 s14, s4, s14
	s_subb_u32 s15, s5, 0
	s_add_u32 s14, s14, 0x3500
	s_addc_u32 s15, s15, 0
	global_load_dword v0, v0, s[14:15] sc1
	s_waitcnt vmcnt(0)
	v_cmp_eq_u32_e32 vcc, v0, v1
	s_and_saveexec_b64 s[10:11], vcc
	s_cbranch_execz .LBB0_1496
	s_add_u32 s12, s2, 0x1d83200
	s_addc_u32 s13, s3, 0
	s_mov_b32 s26, 1
	s_mov_b64 s[16:17], 0
	v_mov_b32_e32 v0, 0
	s_branch .LBB0_1487
